# v39: v32 with the weight-conversion tile stride taken from gridDim instead of a hard-coded 256 (robustness; same schedule)
# speedup vs baseline: 1.0006x; 1.0006x over previous
.Lcw_rows_done:
	s_mov_b32 s31, s2
	s_mov_b32 s32, s2
	s_min_u32 s54, s31, s25
	s_mul_hi_u32 s55, s54, s23
	s_mul_i32 s56, s55, s22
	s_sub_u32 s56, s54, s56
	s_mul_i32 s57, s55, s20
	s_lshl_b32 s56, s56, 8
	s_add_u32 s57, s57, s56
	s_add_u32 s48, s16, s57
	s_addc_u32 s49, s17, 0
	s_lshl_b32 s55, s55, 8
	s_add_u32 s50, s26, s55
	s_addc_u32 s51, s27, 0
	global_load_dword v64, v13, s[48:49]
	global_load_dword v65, v14, s[48:49]
	global_load_dword v66, v15, s[48:49]
	global_load_dword v67, v16, s[48:49]
	global_load_dword v68, v17, s[48:49]
	global_load_dword v69, v18, s[48:49]
	global_load_dword v70, v19, s[48:49]
	global_load_dword v71, v20, s[48:49]
	global_load_dword v88, v21, s[50:51]
	global_load_dword v89, v22, s[50:51]
	global_load_dword v90, v23, s[50:51]
	global_load_dword v91, v24, s[50:51]
	global_load_dword v92, v25, s[50:51]
	global_load_dword v93, v26, s[50:51]
	global_load_dword v94, v27, s[50:51]
	global_load_dword v95, v28, s[50:51]
	s_add_i32 s31, s31, s46
	s_min_u32 s54, s31, s25
	s_mul_hi_u32 s55, s54, s23
	s_mul_i32 s56, s55, s22
	s_sub_u32 s56, s54, s56
	s_mul_i32 s57, s55, s20
	s_lshl_b32 s56, s56, 8
	s_add_u32 s57, s57, s56
	s_add_u32 s48, s16, s57
	s_addc_u32 s49, s17, 0
	s_lshl_b32 s55, s55, 8
	s_add_u32 s50, s26, s55
	s_addc_u32 s51, s27, 0
	global_load_dword v72, v13, s[48:49]
	global_load_dword v73, v14, s[48:49]
	global_load_dword v74, v15, s[48:49]
	global_load_dword v75, v16, s[48:49]
	global_load_dword v76, v17, s[48:49]
	global_load_dword v77, v18, s[48:49]
	global_load_dword v78, v19, s[48:49]
	global_load_dword v79, v20, s[48:49]
	global_load_dword v96, v21, s[50:51]
	global_load_dword v97, v22, s[50:51]
	global_load_dword v98, v23, s[50:51]
	global_load_dword v99, v24, s[50:51]
	global_load_dword v100, v25, s[50:51]
	global_load_dword v101, v26, s[50:51]
	global_load_dword v102, v27, s[50:51]
	global_load_dword v103, v28, s[50:51]
	s_add_i32 s31, s31, s46
.Lcw_loop:
	s_min_u32 s54, s31, s25
	s_mul_hi_u32 s55, s54, s23
	s_mul_i32 s56, s55, s22
	s_sub_u32 s56, s54, s56
	s_mul_i32 s57, s55, s20
	s_lshl_b32 s56, s56, 8
	s_add_u32 s57, s57, s56
	s_add_u32 s48, s16, s57
	s_addc_u32 s49, s17, 0
	s_lshl_b32 s55, s55, 8
	s_add_u32 s50, s26, s55
	s_addc_u32 s51, s27, 0
	global_load_dword v80, v13, s[48:49]
	global_load_dword v81, v14, s[48:49]
	global_load_dword v82, v15, s[48:49]
	global_load_dword v83, v16, s[48:49]
	global_load_dword v84, v17, s[48:49]
	global_load_dword v85, v18, s[48:49]
	global_load_dword v86, v19, s[48:49]
	global_load_dword v87, v20, s[48:49]
	global_load_dword v104, v21, s[50:51]
	global_load_dword v105, v22, s[50:51]
	global_load_dword v106, v23, s[50:51]
	global_load_dword v107, v24, s[50:51]
	global_load_dword v108, v25, s[50:51]
	global_load_dword v109, v26, s[50:51]
	global_load_dword v110, v27, s[50:51]
	global_load_dword v111, v28, s[50:51]
	s_add_i32 s31, s31, s46
	s_waitcnt vmcnt(32)
	s_cmp_eq_u32 s28, 0
	s_cbranch_scc1 .Lcw_nogain_0
	v_mul_f32_e32 v64, v64, v88
	v_mul_f32_e32 v65, v65, v89
	v_mul_f32_e32 v66, v66, v90
	v_mul_f32_e32 v67, v67, v91
	v_mul_f32_e32 v68, v68, v92
	v_mul_f32_e32 v69, v69, v93
	v_mul_f32_e32 v70, v70, v94
	v_mul_f32_e32 v71, v71, v95

.Lcw_np_0:
	s_mul_i32 s57, s57, s21
	s_lshl_b32 s55, s55, 7
	s_add_u32 s57, s57, s55
	s_add_u32 s52, s18, s57
	s_addc_u32 s53, s19, 0
	s_waitcnt lgkmcnt(0)
	s_barrier
	ds_read2_b32 v[46:47], v45 offset0:0 offset1:65
	ds_read2_b32 v[48:49], v45 offset0:16 offset1:81
	ds_read2_b32 v[50:51], v45 offset0:32 offset1:97
	ds_read2_b32 v[52:53], v45 offset0:48 offset1:113
	s_waitcnt lgkmcnt(3)
	v_cvt_pk_bf16_f32 v54, v46, v47
	global_store_dword v40, v54, s[52:53]
	s_waitcnt lgkmcnt(2)
	v_cvt_pk_bf16_f32 v55, v48, v49
	global_store_dword v41, v55, s[52:53]
	s_waitcnt lgkmcnt(1)
	v_cvt_pk_bf16_f32 v56, v50, v51
	global_store_dword v42, v56, s[52:53]
	s_waitcnt lgkmcnt(0)
	v_cvt_pk_bf16_f32 v57, v52, v53
	global_store_dword v43, v57, s[52:53]
	s_xor_b32 s34, s34, 0x4100
	s_add_i32 s32, s32, s46
	s_cmp_ge_u32 s32, s24
	s_cbranch_scc1 .Lcw_done
	s_min_u32 s54, s31, s25
	s_mul_hi_u32 s55, s54, s23
	s_mul_i32 s56, s55, s22
	s_sub_u32 s56, s54, s56
	s_mul_i32 s57, s55, s20
	s_lshl_b32 s56, s56, 8
	s_add_u32 s57, s57, s56
	s_add_u32 s48, s16, s57
	s_addc_u32 s49, s17, 0
	s_lshl_b32 s55, s55, 8
	s_add_u32 s50, s26, s55
	s_addc_u32 s51, s27, 0
	global_load_dword v64, v13, s[48:49]
	global_load_dword v65, v14, s[48:49]
	global_load_dword v66, v15, s[48:49]
	global_load_dword v67, v16, s[48:49]
	global_load_dword v68, v17, s[48:49]
	global_load_dword v69, v18, s[48:49]
	global_load_dword v70, v19, s[48:49]
	global_load_dword v71, v20, s[48:49]
	global_load_dword v88, v21, s[50:51]
	global_load_dword v89, v22, s[50:51]
	global_load_dword v90, v23, s[50:51]
	global_load_dword v91, v24, s[50:51]
	global_load_dword v92, v25, s[50:51]
	global_load_dword v93, v26, s[50:51]
	global_load_dword v94, v27, s[50:51]
	global_load_dword v95, v28, s[50:51]
	s_add_i32 s31, s31, s46
	s_waitcnt vmcnt(32)
	s_cmp_eq_u32 s28, 0
	s_cbranch_scc1 .Lcw_nogain_1
	v_mul_f32_e32 v72, v72, v96
	v_mul_f32_e32 v73, v73, v97
	v_mul_f32_e32 v74, v74, v98
	v_mul_f32_e32 v75, v75, v99
	v_mul_f32_e32 v76, v76, v100
	v_mul_f32_e32 v77, v77, v101
	v_mul_f32_e32 v78, v78, v102
	v_mul_f32_e32 v79, v79, v103

.Lcw_np_1:
	s_mul_i32 s57, s57, s21
	s_lshl_b32 s55, s55, 7
	s_add_u32 s57, s57, s55
	s_add_u32 s52, s18, s57
	s_addc_u32 s53, s19, 0
	s_waitcnt lgkmcnt(0)
	s_barrier
	ds_read2_b32 v[46:47], v45 offset0:0 offset1:65
	ds_read2_b32 v[48:49], v45 offset0:16 offset1:81
	ds_read2_b32 v[50:51], v45 offset0:32 offset1:97
	ds_read2_b32 v[52:53], v45 offset0:48 offset1:113
	s_waitcnt lgkmcnt(3)
	v_cvt_pk_bf16_f32 v54, v46, v47
	global_store_dword v40, v54, s[52:53]
	s_waitcnt lgkmcnt(2)
	v_cvt_pk_bf16_f32 v55, v48, v49
	global_store_dword v41, v55, s[52:53]
	s_waitcnt lgkmcnt(1)
	v_cvt_pk_bf16_f32 v56, v50, v51
	global_store_dword v42, v56, s[52:53]
	s_waitcnt lgkmcnt(0)
	v_cvt_pk_bf16_f32 v57, v52, v53
	global_store_dword v43, v57, s[52:53]
	s_xor_b32 s34, s34, 0x4100
	s_add_i32 s32, s32, s46
	s_cmp_ge_u32 s32, s24
	s_cbranch_scc1 .Lcw_done
	s_min_u32 s54, s31, s25
	s_mul_hi_u32 s55, s54, s23
	s_mul_i32 s56, s55, s22
	s_sub_u32 s56, s54, s56
	s_mul_i32 s57, s55, s20
	s_lshl_b32 s56, s56, 8
	s_add_u32 s57, s57, s56
	s_add_u32 s48, s16, s57
	s_addc_u32 s49, s17, 0
	s_lshl_b32 s55, s55, 8
	s_add_u32 s50, s26, s55
	s_addc_u32 s51, s27, 0
	global_load_dword v72, v13, s[48:49]
	global_load_dword v73, v14, s[48:49]
	global_load_dword v74, v15, s[48:49]
	global_load_dword v75, v16, s[48:49]
	global_load_dword v76, v17, s[48:49]
	global_load_dword v77, v18, s[48:49]
	global_load_dword v78, v19, s[48:49]
	global_load_dword v79, v20, s[48:49]
	global_load_dword v96, v21, s[50:51]
	global_load_dword v97, v22, s[50:51]
	global_load_dword v98, v23, s[50:51]
	global_load_dword v99, v24, s[50:51]
	global_load_dword v100, v25, s[50:51]
	global_load_dword v101, v26, s[50:51]
	global_load_dword v102, v27, s[50:51]
	global_load_dword v103, v28, s[50:51]
	s_add_i32 s31, s31, s46
	s_waitcnt vmcnt(32)
	s_cmp_eq_u32 s28, 0
	s_cbranch_scc1 .Lcw_nogain_2
	v_mul_f32_e32 v80, v80, v104
	v_mul_f32_e32 v81, v81, v105
	v_mul_f32_e32 v82, v82, v106
	v_mul_f32_e32 v83, v83, v107
	v_mul_f32_e32 v84, v84, v108
	v_mul_f32_e32 v85, v85, v109
	v_mul_f32_e32 v86, v86, v110
	v_mul_f32_e32 v87, v87, v111

.Lcw_np_2:
	s_mul_i32 s57, s57, s21
	s_lshl_b32 s55, s55, 7
	s_add_u32 s57, s57, s55
	s_add_u32 s52, s18, s57
	s_addc_u32 s53, s19, 0
	s_waitcnt lgkmcnt(0)
	s_barrier
	ds_read2_b32 v[46:47], v45 offset0:0 offset1:65
	ds_read2_b32 v[48:49], v45 offset0:16 offset1:81
	ds_read2_b32 v[50:51], v45 offset0:32 offset1:97
	ds_read2_b32 v[52:53], v45 offset0:48 offset1:113
	s_waitcnt lgkmcnt(3)
	v_cvt_pk_bf16_f32 v54, v46, v47
	global_store_dword v40, v54, s[52:53]
	s_waitcnt lgkmcnt(2)
	v_cvt_pk_bf16_f32 v55, v48, v49
	global_store_dword v41, v55, s[52:53]
	s_waitcnt lgkmcnt(1)
	v_cvt_pk_bf16_f32 v56, v50, v51
	global_store_dword v42, v56, s[52:53]
	s_waitcnt lgkmcnt(0)
	v_cvt_pk_bf16_f32 v57, v52, v53
	global_store_dword v43, v57, s[52:53]
	s_xor_b32 s34, s34, 0x4100
	s_add_i32 s32, s32, s46
	s_cmp_ge_u32 s32, s24
	s_cbranch_scc1 .Lcw_done
	s_branch .Lcw_loop
